# S5 scan step: the two packed FMAs + v_mov of the complex multiply merged into one packed FMA (addend negated in the low half only); same products and roundings
# baseline (speedup 1.0000x reference)
.LBB0_972:
	s_waitcnt vmcnt(0)
	v_mov_b32_e32 v34, v134
	v_mov_b32_e32 v35, v135
	v_mov_b32_e32 v36, v136
	v_mov_b32_e32 v37, v137
	s_and_saveexec_b64 s[20:21], s[4:5]
	global_load_dwordx4 v[134:137], v[130:131], off
	s_or_b64 exec, exec, s[20:21]
	v_add_co_u32_e32 v130, vcc, 0x4000, v130
	s_nop 1
	v_addc_co_u32_e32 v131, vcc, 0, v131, vcc
	s_waitcnt lgkmcnt(0)
	v_mfma_f32_16x16x32_bf16 v[90:93], v[34:37], v[4:7], 0
	v_add_u32_e32 v71, 0x400, v68
	v_mfma_f32_16x16x32_bf16 v[94:97], v[34:37], v[0:3], 0
	s_nop 7
	ds_write2_b32 v68, v90, v94 offset1:16
	ds_write2_b32 v68, v91, v95 offset0:132 offset1:148
	ds_write2_b32 v71, v92, v96 offset0:8 offset1:24
	ds_write2_b32 v71, v93, v97 offset0:140 offset1:156
	v_mfma_f32_16x16x32_bf16 v[90:93], v[34:37], v[12:15], 0
	v_mfma_f32_16x16x32_bf16 v[94:97], v[34:37], v[8:11], 0
	s_nop 7
	ds_write2_b32 v68, v90, v94 offset0:32 offset1:48
	ds_write2_b32 v68, v91, v95 offset0:164 offset1:180
	ds_write2_b32 v71, v92, v96 offset0:40 offset1:56
	ds_write2_b32 v71, v93, v97 offset0:172 offset1:188
	v_mfma_f32_16x16x32_bf16 v[90:93], v[34:37], v[22:25], 0
	v_mfma_f32_16x16x32_bf16 v[94:97], v[34:37], v[18:21], 0
	s_nop 7
	ds_write2_b32 v68, v90, v94 offset0:64 offset1:80
	ds_write2_b32 v68, v91, v95 offset0:196 offset1:212
	ds_write2_b32 v71, v92, v96 offset0:72 offset1:88
	ds_write2_b32 v71, v93, v97 offset0:204 offset1:220
	v_mfma_f32_16x16x32_bf16 v[90:93], v[34:37], v[30:33], 0
	v_mfma_f32_16x16x32_bf16 v[34:37], v[34:37], v[26:29], 0
	s_nop 7
	ds_write2_b32 v68, v90, v34 offset0:96 offset1:112
	ds_write2_b32 v68, v91, v35 offset0:228 offset1:244
	ds_write2_b32 v71, v92, v36 offset0:104 offset1:120
	ds_write2_b32 v71, v93, v37 offset0:236 offset1:252
	s_waitcnt lgkmcnt(0)
	ds_read_b32 v98, v154 offset:0
	ds_read_b32 v99, v154 offset:256
	ds_read_b32 v100, v154 offset:528
	ds_read_b32 v101, v154 offset:784
	ds_read_b32 v102, v154 offset:1056
	ds_read_b32 v103, v154 offset:1312
	ds_read_b32 v104, v154 offset:1584
	ds_read_b32 v105, v154 offset:1840
	ds_read_b32 v106, v154 offset:2112
	ds_read_b32 v107, v154 offset:2368
	ds_read_b32 v108, v154 offset:2640
	ds_read_b32 v109, v154 offset:2896
	ds_read_b32 v110, v154 offset:3168
	ds_read_b32 v111, v154 offset:3424
	v_pk_mul_f32 v[36:37], v[56:57], v[38:39]
	s_nop 0
	v_pk_fma_f32 v[90:91], v[54:55], v[38:39], v[36:37] op_sel:[0,0,1] op_sel_hi:[1,1,0] neg_lo:[0,0,1]
	s_nop 0
	s_waitcnt lgkmcnt(12)
	v_pk_add_f32 v[38:39], v[90:91], v[98:99]
	ds_read_b32 v112, v154 offset:3696
	ds_read_b32 v113, v154 offset:3952
	v_pk_mul_f32 v[36:37], v[56:57], v[38:39]
	s_nop 0
	v_pk_fma_f32 v[90:91], v[54:55], v[38:39], v[36:37] op_sel:[0,0,1] op_sel_hi:[1,1,0] neg_lo:[0,0,1]
	s_nop 0
	s_waitcnt lgkmcnt(12)
	v_pk_add_f32 v[38:39], v[90:91], v[100:101]
	ds_read_b32 v114, v154 offset:4224
	ds_read_b32 v115, v154 offset:4480
	v_pk_mul_f32 v[36:37], v[56:57], v[38:39]
	s_nop 0
	v_pk_fma_f32 v[90:91], v[54:55], v[38:39], v[36:37] op_sel:[0,0,1] op_sel_hi:[1,1,0] neg_lo:[0,0,1]
	s_nop 0
	s_waitcnt lgkmcnt(12)
	v_pk_add_f32 v[38:39], v[90:91], v[102:103]
	ds_read_b32 v116, v154 offset:4752
	ds_read_b32 v117, v154 offset:5008
	v_pk_mul_f32 v[36:37], v[56:57], v[38:39]
	s_nop 0
	v_pk_fma_f32 v[90:91], v[54:55], v[38:39], v[36:37] op_sel:[0,0,1] op_sel_hi:[1,1,0] neg_lo:[0,0,1]
	s_nop 0
	s_waitcnt lgkmcnt(12)
	v_pk_add_f32 v[38:39], v[90:91], v[104:105]
	ds_read_b32 v118, v154 offset:5280
	ds_read_b32 v119, v154 offset:5536
	v_pk_mul_f32 v[36:37], v[56:57], v[38:39]
	s_nop 0
	v_pk_fma_f32 v[90:91], v[54:55], v[38:39], v[36:37] op_sel:[0,0,1] op_sel_hi:[1,1,0] neg_lo:[0,0,1]
	s_nop 0
	s_waitcnt lgkmcnt(12)
	v_pk_add_f32 v[38:39], v[90:91], v[106:107]
	ds_read_b32 v120, v154 offset:5808
	ds_read_b32 v121, v154 offset:6064
	v_pk_mul_f32 v[36:37], v[56:57], v[38:39]
	s_nop 0
	v_pk_fma_f32 v[90:91], v[54:55], v[38:39], v[36:37] op_sel:[0,0,1] op_sel_hi:[1,1,0] neg_lo:[0,0,1]
	s_nop 0
	s_waitcnt lgkmcnt(12)
	v_pk_add_f32 v[38:39], v[90:91], v[108:109]
	ds_read_b32 v122, v154 offset:6336
	ds_read_b32 v123, v154 offset:6592
	v_pk_mul_f32 v[36:37], v[56:57], v[38:39]
	s_nop 0
	v_pk_fma_f32 v[90:91], v[54:55], v[38:39], v[36:37] op_sel:[0,0,1] op_sel_hi:[1,1,0] neg_lo:[0,0,1]
	s_nop 0
	s_waitcnt lgkmcnt(12)
	v_pk_add_f32 v[38:39], v[90:91], v[110:111]
	ds_read_b32 v124, v154 offset:6864
	ds_read_b32 v125, v154 offset:7120
	v_pk_mul_f32 v[36:37], v[56:57], v[38:39]
	s_nop 0
	v_pk_fma_f32 v[90:91], v[54:55], v[38:39], v[36:37] op_sel:[0,0,1] op_sel_hi:[1,1,0] neg_lo:[0,0,1]
	s_nop 0
	s_waitcnt lgkmcnt(12)
	v_pk_add_f32 v[38:39], v[90:91], v[112:113]
	ds_read_b32 v126, v154 offset:7392
	ds_read_b32 v127, v154 offset:7648
	v_pk_mul_f32 v[36:37], v[56:57], v[38:39]
	s_nop 0
	v_pk_fma_f32 v[90:91], v[54:55], v[38:39], v[36:37] op_sel:[0,0,1] op_sel_hi:[1,1,0] neg_lo:[0,0,1]
	s_nop 0
	s_waitcnt lgkmcnt(12)
	v_pk_add_f32 v[38:39], v[90:91], v[114:115]
	ds_read_b32 v128, v154 offset:7920
	ds_read_b32 v129, v154 offset:8176
	v_pk_mul_f32 v[36:37], v[56:57], v[38:39]
	s_nop 0
	v_pk_fma_f32 v[90:91], v[54:55], v[38:39], v[36:37] op_sel:[0,0,1] op_sel_hi:[1,1,0] neg_lo:[0,0,1]
	s_nop 0
	s_waitcnt lgkmcnt(12)
	v_pk_add_f32 v[38:39], v[90:91], v[116:117]
	v_pk_mul_f32 v[36:37], v[56:57], v[38:39]
	s_nop 0
	v_pk_fma_f32 v[90:91], v[54:55], v[38:39], v[36:37] op_sel:[0,0,1] op_sel_hi:[1,1,0] neg_lo:[0,0,1]
	s_nop 0
	s_waitcnt lgkmcnt(10)
	v_pk_add_f32 v[38:39], v[90:91], v[118:119]
	v_pk_mul_f32 v[36:37], v[56:57], v[38:39]
	s_nop 0
	v_pk_fma_f32 v[90:91], v[54:55], v[38:39], v[36:37] op_sel:[0,0,1] op_sel_hi:[1,1,0] neg_lo:[0,0,1]
	s_nop 0
	s_waitcnt lgkmcnt(8)
	v_pk_add_f32 v[38:39], v[90:91], v[120:121]
	v_pk_mul_f32 v[36:37], v[56:57], v[38:39]
	s_nop 0
	v_pk_fma_f32 v[90:91], v[54:55], v[38:39], v[36:37] op_sel:[0,0,1] op_sel_hi:[1,1,0] neg_lo:[0,0,1]
	s_nop 0
	s_waitcnt lgkmcnt(6)
	v_pk_add_f32 v[38:39], v[90:91], v[122:123]
	v_pk_mul_f32 v[36:37], v[56:57], v[38:39]
	s_nop 0
	v_pk_fma_f32 v[90:91], v[54:55], v[38:39], v[36:37] op_sel:[0,0,1] op_sel_hi:[1,1,0] neg_lo:[0,0,1]
	s_nop 0
	s_waitcnt lgkmcnt(4)
	v_pk_add_f32 v[38:39], v[90:91], v[124:125]
	v_pk_mul_f32 v[36:37], v[56:57], v[38:39]
	s_nop 0
	v_pk_fma_f32 v[90:91], v[54:55], v[38:39], v[36:37] op_sel:[0,0,1] op_sel_hi:[1,1,0] neg_lo:[0,0,1]
	s_nop 0
	s_waitcnt lgkmcnt(2)
	v_pk_add_f32 v[38:39], v[90:91], v[126:127]
	v_pk_mul_f32 v[36:37], v[56:57], v[38:39]
	s_nop 0
	v_pk_fma_f32 v[90:91], v[54:55], v[38:39], v[36:37] op_sel:[0,0,1] op_sel_hi:[1,1,0] neg_lo:[0,0,1]
	s_nop 0
	s_waitcnt lgkmcnt(0)
	v_pk_add_f32 v[38:39], v[90:91], v[128:129]
	s_add_i32 s38, s38, 1
	s_cmp_eq_u32 s38, 4
	s_cbranch_scc0 .LBB0_972
	v_or_b32_e32 v16, s37, v64
	s_add_i32 s36, s36, 1
	v_lshl_add_u32 v16, v16, 3, 0
	s_cmp_eq_u32 s36, 4
	ds_write_b64 v16, v[38:39]
	s_cbranch_scc0 .LBB0_971
	s_andn2_b64 vcc, exec, s[2:3]
	s_waitcnt lgkmcnt(0)
	s_barrier
	s_cbranch_vccnz .LBB0_980
	v_mov_b32_e32 v34, v56
	v_mov_b32_e32 v35, v55
	v_pk_mul_f32 v[36:37], v[34:35], v[34:35] op_sel:[1,0] op_sel_hi:[0,0]
	v_pk_fma_f32 v[38:39], v[54:55], v[34:35], v[36:37]
	v_pk_fma_f32 v[34:35], v[54:55], v[34:35], v[36:37] neg_lo:[0,0,1] neg_hi:[0,0,1]
	v_mov_b32_e32 v36, v38
	v_pk_mov_b32 v[88:89], v[34:35], v[38:39] op_sel:[1,0]
	v_mov_b32_e32 v37, v35
	v_pk_mul_f32 v[38:39], v[38:39], v[88:89] op_sel_hi:[0,1]
	v_pk_fma_f32 v[88:89], v[36:37], v[34:35], v[38:39] op_sel:[0,1,0]
	v_pk_fma_f32 v[34:35], v[36:37], v[34:35], v[38:39] op_sel:[0,1,0] neg_lo:[0,0,1] neg_hi:[0,0,1]
	v_mov_b32_e32 v36, v88
	v_pk_mov_b32 v[38:39], v[34:35], v[88:89] op_sel:[1,0]
	v_mov_b32_e32 v37, v35
	v_pk_mul_f32 v[38:39], v[88:89], v[38:39] op_sel_hi:[0,1]
	v_pk_fma_f32 v[88:89], v[36:37], v[34:35], v[38:39] op_sel:[0,1,0]
	v_pk_fma_f32 v[34:35], v[36:37], v[34:35], v[38:39] op_sel:[0,1,0] neg_lo:[0,0,1] neg_hi:[0,0,1]
	v_mov_b32_e32 v36, v88
	v_pk_mov_b32 v[38:39], v[34:35], v[88:89] op_sel:[1,0]
	v_mov_b32_e32 v37, v35
	v_pk_mul_f32 v[38:39], v[88:89], v[38:39] op_sel_hi:[0,1]
	v_pk_fma_f32 v[88:89], v[36:37], v[34:35], v[38:39] op_sel:[0,1,0]
	v_pk_fma_f32 v[34:35], v[36:37], v[34:35], v[38:39] op_sel:[0,1,0] neg_lo:[0,0,1] neg_hi:[0,0,1]
	v_mov_b32_e32 v36, v88
	v_pk_mov_b32 v[38:39], v[34:35], v[88:89] op_sel:[1,0]
	v_mov_b32_e32 v37, v35
	v_pk_mul_f32 v[38:39], v[88:89], v[38:39] op_sel_hi:[0,1]
	v_pk_fma_f32 v[88:89], v[88:89], v[34:35], v[38:39] op_sel:[0,1,0]
	v_pk_fma_f32 v[36:37], v[36:37], v[34:35], v[38:39] op_sel:[0,1,0] neg_lo:[0,0,1] neg_hi:[0,0,1]
	v_lshl_add_u32 v38, v64, 3, 0
	v_mov_b32_e32 v89, v37
	v_mul_f32_e32 v16, v37, v37
	v_pk_fma_f32 v[34:35], v[88:89], v[88:89], v[16:17] op_sel_hi:[1,1,0] neg_lo:[1,0,0] neg_hi:[1,0,0]
	v_pk_mul_f32 v[36:37], v[88:89], v[36:37] op_sel:[0,1] op_sel_hi:[1,0]
	ds_read2st64_b64 v[88:91], v38 offset1:1
	v_pk_add_f32 v[36:37], v[36:37], v[36:37]
	v_mul_f32_e32 v39, 0, v34
	v_mul_f32_e32 v93, 0, v36
	v_sub_f32_e32 v92, v39, v93
	v_fmac_f32_e32 v93, 0, v34
	s_waitcnt lgkmcnt(0)
	v_pk_add_f32 v[88:89], v[92:93], v[88:89]
	v_mov_b32_e32 v16, v17
	v_pk_mul_f32 v[92:93], v[36:37], v[88:89] op_sel_hi:[0,1]
	ds_write2st64_b64 v38, v[16:17], v[88:89] offset1:1
	v_pk_fma_f32 v[94:95], v[34:35], v[88:89], v[92:93] op_sel:[0,0,1] op_sel_hi:[1,1,0] neg_lo:[0,0,1] neg_hi:[0,0,1]
	v_pk_fma_f32 v[88:89], v[34:35], v[88:89], v[92:93] op_sel:[0,0,1] op_sel_hi:[0,1,0]
	v_mov_b32_e32 v95, v89
	v_pk_add_f32 v[92:93], v[94:95], v[90:91]
	ds_read2st64_b64 v[88:91], v38 offset0:2 offset1:3
	v_pk_mul_f32 v[94:95], v[36:37], v[92:93] op_sel_hi:[0,1]
	v_pk_fma_f32 v[96:97], v[34:35], v[92:93], v[94:95] op_sel:[0,0,1] op_sel_hi:[1,1,0] neg_lo:[0,0,1] neg_hi:[0,0,1]
	v_pk_fma_f32 v[94:95], v[34:35], v[92:93], v[94:95] op_sel:[0,0,1] op_sel_hi:[0,1,0]
	v_mov_b32_e32 v97, v95
	s_waitcnt lgkmcnt(0)
	v_pk_add_f32 v[88:89], v[96:97], v[88:89]
	ds_write2st64_b64 v38, v[92:93], v[88:89] offset0:2 offset1:3
	v_pk_mul_f32 v[92:93], v[36:37], v[88:89] op_sel_hi:[0,1]
	v_pk_fma_f32 v[94:95], v[34:35], v[88:89], v[92:93] op_sel:[0,0,1] op_sel_hi:[1,1,0] neg_lo:[0,0,1] neg_hi:[0,0,1]
	v_pk_fma_f32 v[88:89], v[34:35], v[88:89], v[92:93] op_sel:[0,0,1] op_sel_hi:[0,1,0]
	v_mov_b32_e32 v95, v89
	v_pk_add_f32 v[92:93], v[94:95], v[90:91]
	ds_read2st64_b64 v[88:91], v38 offset0:4 offset1:5
	v_pk_mul_f32 v[94:95], v[36:37], v[92:93] op_sel_hi:[0,1]
	v_pk_fma_f32 v[96:97], v[34:35], v[92:93], v[94:95] op_sel:[0,0,1] op_sel_hi:[1,1,0] neg_lo:[0,0,1] neg_hi:[0,0,1]
	v_pk_fma_f32 v[94:95], v[34:35], v[92:93], v[94:95] op_sel:[0,0,1] op_sel_hi:[0,1,0]
	v_mov_b32_e32 v97, v95
	s_waitcnt lgkmcnt(0)
	v_pk_add_f32 v[88:89], v[96:97], v[88:89]
	ds_write2st64_b64 v38, v[92:93], v[88:89] offset0:4 offset1:5
	v_pk_mul_f32 v[92:93], v[36:37], v[88:89] op_sel_hi:[0,1]
	v_pk_fma_f32 v[94:95], v[34:35], v[88:89], v[92:93] op_sel:[0,0,1] op_sel_hi:[1,1,0] neg_lo:[0,0,1] neg_hi:[0,0,1]
	v_pk_fma_f32 v[88:89], v[34:35], v[88:89], v[92:93] op_sel:[0,0,1] op_sel_hi:[0,1,0]
	v_mov_b32_e32 v95, v89
	v_pk_add_f32 v[92:93], v[94:95], v[90:91]
	ds_read2st64_b64 v[88:91], v38 offset0:6 offset1:7
	v_pk_mul_f32 v[94:95], v[36:37], v[92:93] op_sel_hi:[0,1]
	v_pk_fma_f32 v[96:97], v[34:35], v[92:93], v[94:95] op_sel:[0,0,1] op_sel_hi:[1,1,0] neg_lo:[0,0,1] neg_hi:[0,0,1]
	v_pk_fma_f32 v[94:95], v[34:35], v[92:93], v[94:95] op_sel:[0,0,1] op_sel_hi:[0,1,0]
	v_mov_b32_e32 v97, v95
	s_waitcnt lgkmcnt(0)
	v_pk_add_f32 v[88:89], v[96:97], v[88:89]
	ds_write2st64_b64 v38, v[92:93], v[88:89] offset0:6 offset1:7
	v_pk_mul_f32 v[92:93], v[36:37], v[88:89] op_sel_hi:[0,1]
	v_pk_fma_f32 v[94:95], v[34:35], v[88:89], v[92:93] op_sel:[0,0,1] op_sel_hi:[1,1,0] neg_lo:[0,0,1] neg_hi:[0,0,1]
	v_pk_fma_f32 v[88:89], v[34:35], v[88:89], v[92:93] op_sel:[0,0,1] op_sel_hi:[0,1,0]
	v_mov_b32_e32 v95, v89
	v_pk_add_f32 v[92:93], v[94:95], v[90:91]
	ds_read2st64_b64 v[88:91], v38 offset0:8 offset1:9
	v_pk_mul_f32 v[94:95], v[36:37], v[92:93] op_sel_hi:[0,1]
	v_pk_fma_f32 v[96:97], v[34:35], v[92:93], v[94:95] op_sel:[0,0,1] op_sel_hi:[1,1,0] neg_lo:[0,0,1] neg_hi:[0,0,1]
	v_pk_fma_f32 v[94:95], v[34:35], v[92:93], v[94:95] op_sel:[0,0,1] op_sel_hi:[0,1,0]
	v_mov_b32_e32 v97, v95
	s_waitcnt lgkmcnt(0)
	v_pk_add_f32 v[88:89], v[96:97], v[88:89]
	ds_write2st64_b64 v38, v[92:93], v[88:89] offset0:8 offset1:9
	v_pk_mul_f32 v[92:93], v[36:37], v[88:89] op_sel_hi:[0,1]
	v_pk_fma_f32 v[94:95], v[34:35], v[88:89], v[92:93] op_sel:[0,0,1] op_sel_hi:[1,1,0] neg_lo:[0,0,1] neg_hi:[0,0,1]
	v_pk_fma_f32 v[88:89], v[34:35], v[88:89], v[92:93] op_sel:[0,0,1] op_sel_hi:[0,1,0]
	v_mov_b32_e32 v95, v89
	v_pk_add_f32 v[92:93], v[94:95], v[90:91]
	ds_read2st64_b64 v[88:91], v38 offset0:10 offset1:11
	v_pk_mul_f32 v[94:95], v[36:37], v[92:93] op_sel_hi:[0,1]
	v_pk_fma_f32 v[96:97], v[34:35], v[92:93], v[94:95] op_sel:[0,0,1] op_sel_hi:[1,1,0] neg_lo:[0,0,1] neg_hi:[0,0,1]
	v_pk_fma_f32 v[94:95], v[34:35], v[92:93], v[94:95] op_sel:[0,0,1] op_sel_hi:[0,1,0]
	v_mov_b32_e32 v97, v95
	s_waitcnt lgkmcnt(0)
	v_pk_add_f32 v[88:89], v[96:97], v[88:89]
	ds_write2st64_b64 v38, v[92:93], v[88:89] offset0:10 offset1:11
	v_pk_mul_f32 v[92:93], v[36:37], v[88:89] op_sel_hi:[0,1]
	v_pk_fma_f32 v[94:95], v[34:35], v[88:89], v[92:93] op_sel:[0,0,1] op_sel_hi:[1,1,0] neg_lo:[0,0,1] neg_hi:[0,0,1]
	v_pk_fma_f32 v[88:89], v[34:35], v[88:89], v[92:93] op_sel:[0,0,1] op_sel_hi:[0,1,0]
	v_mov_b32_e32 v95, v89
	v_pk_add_f32 v[92:93], v[94:95], v[90:91]
	ds_read2st64_b64 v[88:91], v38 offset0:12 offset1:13
	v_pk_mul_f32 v[94:95], v[36:37], v[92:93] op_sel_hi:[0,1]
	v_pk_fma_f32 v[96:97], v[34:35], v[92:93], v[94:95] op_sel:[0,0,1] op_sel_hi:[1,1,0] neg_lo:[0,0,1] neg_hi:[0,0,1]
	v_pk_fma_f32 v[94:95], v[34:35], v[92:93], v[94:95] op_sel:[0,0,1] op_sel_hi:[0,1,0]
	v_mov_b32_e32 v97, v95
	s_waitcnt lgkmcnt(0)
	v_pk_add_f32 v[88:89], v[96:97], v[88:89]
	ds_write2st64_b64 v38, v[92:93], v[88:89] offset0:12 offset1:13
	v_pk_mul_f32 v[92:93], v[36:37], v[88:89] op_sel_hi:[0,1]
	v_pk_fma_f32 v[94:95], v[34:35], v[88:89], v[92:93] op_sel:[0,0,1] op_sel_hi:[1,1,0] neg_lo:[0,0,1] neg_hi:[0,0,1]
	v_pk_fma_f32 v[88:89], v[34:35], v[88:89], v[92:93] op_sel:[0,0,1] op_sel_hi:[0,1,0]
	v_mov_b32_e32 v95, v89
	v_pk_add_f32 v[92:93], v[94:95], v[90:91]
	ds_read2st64_b64 v[88:91], v38 offset0:14 offset1:15
	v_pk_mul_f32 v[94:95], v[36:37], v[92:93] op_sel_hi:[0,1]
	v_pk_fma_f32 v[96:97], v[34:35], v[92:93], v[94:95] op_sel:[0,0,1] op_sel_hi:[1,1,0] neg_lo:[0,0,1] neg_hi:[0,0,1]
	v_pk_fma_f32 v[94:95], v[34:35], v[92:93], v[94:95] op_sel:[0,0,1] op_sel_hi:[0,1,0]
	v_mov_b32_e32 v97, v95
	s_waitcnt lgkmcnt(0)
	v_pk_add_f32 v[88:89], v[96:97], v[88:89]
	ds_write2st64_b64 v38, v[92:93], v[88:89] offset0:14 offset1:15
	v_pk_mul_f32 v[92:93], v[36:37], v[88:89] op_sel_hi:[0,1]
	v_pk_fma_f32 v[94:95], v[34:35], v[88:89], v[92:93] op_sel:[0,0,1] op_sel_hi:[1,1,0] neg_lo:[0,0,1] neg_hi:[0,0,1]
	v_pk_fma_f32 v[88:89], v[34:35], v[88:89], v[92:93] op_sel:[0,0,1] op_sel_hi:[0,1,0]
	v_mov_b32_e32 v95, v89
	v_pk_add_f32 v[92:93], v[94:95], v[90:91]
	ds_read2st64_b64 v[88:91], v38 offset0:16 offset1:17
	v_pk_mul_f32 v[94:95], v[36:37], v[92:93] op_sel_hi:[0,1]
	v_pk_fma_f32 v[96:97], v[34:35], v[92:93], v[94:95] op_sel:[0,0,1] op_sel_hi:[1,1,0] neg_lo:[0,0,1] neg_hi:[0,0,1]
	v_pk_fma_f32 v[94:95], v[34:35], v[92:93], v[94:95] op_sel:[0,0,1] op_sel_hi:[0,1,0]
	v_mov_b32_e32 v97, v95
	s_waitcnt lgkmcnt(0)
	v_pk_add_f32 v[88:89], v[96:97], v[88:89]
	ds_write2st64_b64 v38, v[92:93], v[88:89] offset0:16 offset1:17
	v_pk_mul_f32 v[92:93], v[36:37], v[88:89] op_sel_hi:[0,1]
	v_pk_fma_f32 v[94:95], v[34:35], v[88:89], v[92:93] op_sel:[0,0,1] op_sel_hi:[1,1,0] neg_lo:[0,0,1] neg_hi:[0,0,1]
	v_pk_fma_f32 v[88:89], v[34:35], v[88:89], v[92:93] op_sel:[0,0,1] op_sel_hi:[0,1,0]
	v_mov_b32_e32 v95, v89
	v_pk_add_f32 v[92:93], v[94:95], v[90:91]
	ds_read2st64_b64 v[88:91], v38 offset0:18 offset1:19
	v_pk_mul_f32 v[94:95], v[36:37], v[92:93] op_sel_hi:[0,1]
	v_pk_fma_f32 v[96:97], v[34:35], v[92:93], v[94:95] op_sel:[0,0,1] op_sel_hi:[1,1,0] neg_lo:[0,0,1] neg_hi:[0,0,1]
	v_pk_fma_f32 v[94:95], v[34:35], v[92:93], v[94:95] op_sel:[0,0,1] op_sel_hi:[0,1,0]
	v_mov_b32_e32 v97, v95
	s_waitcnt lgkmcnt(0)
	v_pk_add_f32 v[88:89], v[96:97], v[88:89]
	ds_write2st64_b64 v38, v[92:93], v[88:89] offset0:18 offset1:19
	v_pk_mul_f32 v[92:93], v[36:37], v[88:89] op_sel_hi:[0,1]
	v_pk_fma_f32 v[94:95], v[34:35], v[88:89], v[92:93] op_sel:[0,0,1] op_sel_hi:[1,1,0] neg_lo:[0,0,1] neg_hi:[0,0,1]
	v_pk_fma_f32 v[88:89], v[34:35], v[88:89], v[92:93] op_sel:[0,0,1] op_sel_hi:[0,1,0]
	v_mov_b32_e32 v95, v89
	v_pk_add_f32 v[92:93], v[94:95], v[90:91]
	ds_read2st64_b64 v[88:91], v38 offset0:20 offset1:21
	v_pk_mul_f32 v[94:95], v[36:37], v[92:93] op_sel_hi:[0,1]
	v_pk_fma_f32 v[96:97], v[34:35], v[92:93], v[94:95] op_sel:[0,0,1] op_sel_hi:[1,1,0] neg_lo:[0,0,1] neg_hi:[0,0,1]
	v_pk_fma_f32 v[94:95], v[34:35], v[92:93], v[94:95] op_sel:[0,0,1] op_sel_hi:[0,1,0]
	v_mov_b32_e32 v97, v95
	s_waitcnt lgkmcnt(0)
	v_pk_add_f32 v[88:89], v[96:97], v[88:89]
	ds_write2st64_b64 v38, v[92:93], v[88:89] offset0:20 offset1:21
	v_pk_mul_f32 v[92:93], v[36:37], v[88:89] op_sel_hi:[0,1]
	v_pk_fma_f32 v[94:95], v[34:35], v[88:89], v[92:93] op_sel:[0,0,1] op_sel_hi:[1,1,0] neg_lo:[0,0,1] neg_hi:[0,0,1]
	v_pk_fma_f32 v[88:89], v[34:35], v[88:89], v[92:93] op_sel:[0,0,1] op_sel_hi:[0,1,0]
	v_mov_b32_e32 v95, v89
	v_pk_add_f32 v[92:93], v[94:95], v[90:91]
	ds_read2st64_b64 v[88:91], v38 offset0:22 offset1:23
	v_pk_mul_f32 v[94:95], v[36:37], v[92:93] op_sel_hi:[0,1]
	v_pk_fma_f32 v[96:97], v[34:35], v[92:93], v[94:95] op_sel:[0,0,1] op_sel_hi:[1,1,0] neg_lo:[0,0,1] neg_hi:[0,0,1]
	v_pk_fma_f32 v[94:95], v[34:35], v[92:93], v[94:95] op_sel:[0,0,1] op_sel_hi:[0,1,0]
	v_mov_b32_e32 v97, v95
	s_waitcnt lgkmcnt(0)
	v_pk_add_f32 v[88:89], v[96:97], v[88:89]
	ds_write2st64_b64 v38, v[92:93], v[88:89] offset0:22 offset1:23
	v_pk_mul_f32 v[92:93], v[36:37], v[88:89] op_sel_hi:[0,1]
	v_pk_fma_f32 v[94:95], v[34:35], v[88:89], v[92:93] op_sel:[0,0,1] op_sel_hi:[1,1,0] neg_lo:[0,0,1] neg_hi:[0,0,1]
	v_pk_fma_f32 v[88:89], v[34:35], v[88:89], v[92:93] op_sel:[0,0,1] op_sel_hi:[0,1,0]
	v_mov_b32_e32 v95, v89
	v_pk_add_f32 v[92:93], v[94:95], v[90:91]
	ds_read2st64_b64 v[88:91], v38 offset0:24 offset1:25
	v_pk_mul_f32 v[94:95], v[36:37], v[92:93] op_sel_hi:[0,1]
	v_pk_fma_f32 v[96:97], v[34:35], v[92:93], v[94:95] op_sel:[0,0,1] op_sel_hi:[1,1,0] neg_lo:[0,0,1] neg_hi:[0,0,1]
	v_pk_fma_f32 v[94:95], v[34:35], v[92:93], v[94:95] op_sel:[0,0,1] op_sel_hi:[0,1,0]
	v_mov_b32_e32 v97, v95
	s_waitcnt lgkmcnt(0)
	v_pk_add_f32 v[88:89], v[96:97], v[88:89]
	ds_write2st64_b64 v38, v[92:93], v[88:89] offset0:24 offset1:25
	v_pk_mul_f32 v[92:93], v[36:37], v[88:89] op_sel_hi:[0,1]
	v_pk_fma_f32 v[94:95], v[34:35], v[88:89], v[92:93] op_sel:[0,0,1] op_sel_hi:[1,1,0] neg_lo:[0,0,1] neg_hi:[0,0,1]
	v_pk_fma_f32 v[88:89], v[34:35], v[88:89], v[92:93] op_sel:[0,0,1] op_sel_hi:[0,1,0]
	v_mov_b32_e32 v95, v89
	v_pk_add_f32 v[92:93], v[94:95], v[90:91]
	ds_read2st64_b64 v[88:91], v38 offset0:26 offset1:27
	v_pk_mul_f32 v[94:95], v[36:37], v[92:93] op_sel_hi:[0,1]
	v_pk_fma_f32 v[96:97], v[34:35], v[92:93], v[94:95] op_sel:[0,0,1] op_sel_hi:[1,1,0] neg_lo:[0,0,1] neg_hi:[0,0,1]
	v_pk_fma_f32 v[94:95], v[34:35], v[92:93], v[94:95] op_sel:[0,0,1] op_sel_hi:[0,1,0]
	v_mov_b32_e32 v97, v95
	s_waitcnt lgkmcnt(0)
	v_pk_add_f32 v[88:89], v[96:97], v[88:89]
	ds_write2st64_b64 v38, v[92:93], v[88:89] offset0:26 offset1:27
	v_pk_mul_f32 v[92:93], v[36:37], v[88:89] op_sel_hi:[0,1]
	v_pk_fma_f32 v[94:95], v[34:35], v[88:89], v[92:93] op_sel:[0,0,1] op_sel_hi:[1,1,0] neg_lo:[0,0,1] neg_hi:[0,0,1]
	v_pk_fma_f32 v[88:89], v[34:35], v[88:89], v[92:93] op_sel:[0,0,1] op_sel_hi:[0,1,0]
	v_mov_b32_e32 v95, v89
	v_pk_add_f32 v[92:93], v[94:95], v[90:91]
	ds_read2st64_b64 v[88:91], v38 offset0:28 offset1:29
	v_pk_mul_f32 v[94:95], v[36:37], v[92:93] op_sel_hi:[0,1]
	v_pk_fma_f32 v[96:97], v[34:35], v[92:93], v[94:95] op_sel:[0,0,1] op_sel_hi:[1,1,0] neg_lo:[0,0,1] neg_hi:[0,0,1]
	v_pk_fma_f32 v[94:95], v[34:35], v[92:93], v[94:95] op_sel:[0,0,1] op_sel_hi:[0,1,0]
	v_mov_b32_e32 v97, v95
	s_waitcnt lgkmcnt(0)
	v_pk_add_f32 v[88:89], v[96:97], v[88:89]
	ds_write2st64_b64 v38, v[92:93], v[88:89] offset0:28 offset1:29
	v_pk_mul_f32 v[92:93], v[36:37], v[88:89] op_sel_hi:[0,1]
	v_pk_fma_f32 v[94:95], v[34:35], v[88:89], v[92:93] op_sel:[0,0,1] op_sel_hi:[1,1,0] neg_lo:[0,0,1] neg_hi:[0,0,1]
	v_pk_fma_f32 v[88:89], v[34:35], v[88:89], v[92:93] op_sel:[0,0,1] op_sel_hi:[0,1,0]
	v_mov_b32_e32 v95, v89
	v_pk_add_f32 v[88:89], v[94:95], v[90:91]
	ds_read_b64 v[90:91], v38 offset:15360
	v_pk_mul_f32 v[36:37], v[36:37], v[88:89] op_sel_hi:[0,1]
	v_pk_fma_f32 v[92:93], v[34:35], v[88:89], v[36:37] op_sel:[0,0,1] op_sel_hi:[1,1,0] neg_lo:[0,0,1] neg_hi:[0,0,1]
	v_pk_fma_f32 v[34:35], v[34:35], v[88:89], v[36:37] op_sel:[0,0,1] op_sel_hi:[0,1,0]
	v_mov_b32_e32 v93, v35
	s_waitcnt lgkmcnt(0)
	v_pk_add_f32 v[34:35], v[92:93], v[90:91]
	ds_write2st64_b64 v38, v[88:89], v[34:35] offset0:30 offset1:31

.LBB0_982:
	s_waitcnt vmcnt(4)
	v_mov_b32_e32 v50, v134
	v_mov_b32_e32 v51, v135
	v_mov_b32_e32 v52, v136
	v_mov_b32_e32 v53, v137
	s_and_saveexec_b64 s[2:3], s[4:5]
	global_load_dwordx4 v[134:137], v[130:131], off
	s_or_b64 exec, exec, s[2:3]
	v_add_co_u32_e32 v130, vcc, 0x4000, v130
	s_nop 1
	v_addc_co_u32_e32 v131, vcc, 0, v131, vcc
	v_mfma_f32_16x16x32_bf16 v[72:75], v[50:53], v[4:7], 0
	v_mfma_f32_16x16x32_bf16 v[76:79], v[50:53], v[0:3], 0
	s_nop 7
	ds_write2_b32 v68, v72, v76 offset1:16
	ds_write2_b32 v68, v73, v77 offset0:132 offset1:148
	ds_write2_b32 v71, v74, v78 offset0:8 offset1:24
	ds_write2_b32 v71, v75, v79 offset0:140 offset1:156
	v_mfma_f32_16x16x32_bf16 v[72:75], v[50:53], v[12:15], 0
	v_mfma_f32_16x16x32_bf16 v[76:79], v[50:53], v[8:11], 0
	s_nop 7
	ds_write2_b32 v68, v72, v76 offset0:32 offset1:48
	ds_write2_b32 v68, v73, v77 offset0:164 offset1:180
	ds_write2_b32 v71, v74, v78 offset0:40 offset1:56
	ds_write2_b32 v71, v75, v79 offset0:172 offset1:188
	v_mfma_f32_16x16x32_bf16 v[72:75], v[50:53], v[22:25], 0
	v_mfma_f32_16x16x32_bf16 v[76:79], v[50:53], v[18:21], 0
	s_nop 7
	ds_write2_b32 v68, v72, v76 offset0:64 offset1:80
	ds_write2_b32 v68, v73, v77 offset0:196 offset1:212
	ds_write2_b32 v71, v74, v78 offset0:72 offset1:88
	ds_write2_b32 v71, v75, v79 offset0:204 offset1:220
	v_mfma_f32_16x16x32_bf16 v[72:75], v[50:53], v[30:33], 0
	v_mfma_f32_16x16x32_bf16 v[50:53], v[50:53], v[26:29], 0
	s_nop 7
	ds_write2_b32 v68, v72, v50 offset0:96 offset1:112
	ds_write2_b32 v68, v73, v51 offset0:228 offset1:244
	ds_write2_b32 v71, v74, v52 offset0:104 offset1:120
	ds_write2_b32 v71, v75, v53 offset0:236 offset1:252
	s_waitcnt lgkmcnt(0)
	ds_read_b32 v98, v154 offset:0
	ds_read_b32 v99, v154 offset:256
	ds_read_b32 v100, v154 offset:528
	ds_read_b32 v101, v154 offset:784
	ds_read_b32 v102, v154 offset:1056
	ds_read_b32 v103, v154 offset:1312
	ds_read_b32 v104, v154 offset:1584
	ds_read_b32 v105, v154 offset:1840
	ds_read_b32 v106, v154 offset:2112
	ds_read_b32 v107, v154 offset:2368
	ds_read_b32 v108, v154 offset:2640
	ds_read_b32 v109, v154 offset:2896
	ds_read_b32 v110, v154 offset:3168
	ds_read_b32 v111, v154 offset:3424
	v_pk_mul_f32 v[52:53], v[56:57], v[62:63]
	s_nop 0
	v_pk_fma_f32 v[72:73], v[54:55], v[62:63], v[52:53] op_sel:[0,0,1] op_sel_hi:[1,1,0] neg_lo:[0,0,1]
	s_nop 0
	s_waitcnt lgkmcnt(12)
	v_pk_add_f32 v[62:63], v[72:73], v[98:99]
	ds_read_b32 v112, v154 offset:3696
	ds_read_b32 v113, v154 offset:3952
	s_nop 0
	v_cvt_pk_bf16_f32 v138, v62, v63
	v_pk_mul_f32 v[52:53], v[56:57], v[62:63]
	s_nop 0
	v_pk_fma_f32 v[72:73], v[54:55], v[62:63], v[52:53] op_sel:[0,0,1] op_sel_hi:[1,1,0] neg_lo:[0,0,1]
	s_nop 0
	s_waitcnt lgkmcnt(12)
	v_pk_add_f32 v[62:63], v[72:73], v[100:101]
	ds_read_b32 v114, v154 offset:4224
	ds_read_b32 v115, v154 offset:4480
	s_nop 0
	v_cvt_pk_bf16_f32 v139, v62, v63
	v_pk_mul_f32 v[52:53], v[56:57], v[62:63]
	s_nop 0
	v_pk_fma_f32 v[72:73], v[54:55], v[62:63], v[52:53] op_sel:[0,0,1] op_sel_hi:[1,1,0] neg_lo:[0,0,1]
	s_nop 0
	s_waitcnt lgkmcnt(12)
	v_pk_add_f32 v[62:63], v[72:73], v[102:103]
	ds_read_b32 v116, v154 offset:4752
	ds_read_b32 v117, v154 offset:5008
	s_nop 0
	v_cvt_pk_bf16_f32 v140, v62, v63
	v_pk_mul_f32 v[52:53], v[56:57], v[62:63]
	s_nop 0
	v_pk_fma_f32 v[72:73], v[54:55], v[62:63], v[52:53] op_sel:[0,0,1] op_sel_hi:[1,1,0] neg_lo:[0,0,1]
	s_nop 0
	s_waitcnt lgkmcnt(12)
	v_pk_add_f32 v[62:63], v[72:73], v[104:105]
	ds_read_b32 v118, v154 offset:5280
	ds_read_b32 v119, v154 offset:5536
	s_nop 0
	v_cvt_pk_bf16_f32 v141, v62, v63
	v_pk_mul_f32 v[52:53], v[56:57], v[62:63]
	s_nop 0
	v_pk_fma_f32 v[72:73], v[54:55], v[62:63], v[52:53] op_sel:[0,0,1] op_sel_hi:[1,1,0] neg_lo:[0,0,1]
	s_nop 0
	s_waitcnt lgkmcnt(12)
	v_pk_add_f32 v[62:63], v[72:73], v[106:107]
	ds_read_b32 v120, v154 offset:5808
	ds_read_b32 v121, v154 offset:6064
	s_nop 0
	v_cvt_pk_bf16_f32 v142, v62, v63
	v_pk_mul_f32 v[52:53], v[56:57], v[62:63]
	s_nop 0
	v_pk_fma_f32 v[72:73], v[54:55], v[62:63], v[52:53] op_sel:[0,0,1] op_sel_hi:[1,1,0] neg_lo:[0,0,1]
	s_nop 0
	s_waitcnt lgkmcnt(12)
	v_pk_add_f32 v[62:63], v[72:73], v[108:109]
	ds_read_b32 v122, v154 offset:6336
	ds_read_b32 v123, v154 offset:6592
	s_nop 0
	v_cvt_pk_bf16_f32 v143, v62, v63
	v_pk_mul_f32 v[52:53], v[56:57], v[62:63]
	s_nop 0
	v_pk_fma_f32 v[72:73], v[54:55], v[62:63], v[52:53] op_sel:[0,0,1] op_sel_hi:[1,1,0] neg_lo:[0,0,1]
	s_nop 0
	s_waitcnt lgkmcnt(12)
	v_pk_add_f32 v[62:63], v[72:73], v[110:111]
	ds_read_b32 v124, v154 offset:6864
	ds_read_b32 v125, v154 offset:7120
	s_nop 0
	v_cvt_pk_bf16_f32 v144, v62, v63
	v_pk_mul_f32 v[52:53], v[56:57], v[62:63]
	s_nop 0
	v_pk_fma_f32 v[72:73], v[54:55], v[62:63], v[52:53] op_sel:[0,0,1] op_sel_hi:[1,1,0] neg_lo:[0,0,1]
	s_nop 0
	s_waitcnt lgkmcnt(12)
	v_pk_add_f32 v[62:63], v[72:73], v[112:113]
	ds_read_b32 v126, v154 offset:7392
	ds_read_b32 v127, v154 offset:7648
	s_nop 0
	v_cvt_pk_bf16_f32 v145, v62, v63
	v_pk_mul_f32 v[52:53], v[56:57], v[62:63]
	s_nop 0
	v_pk_fma_f32 v[72:73], v[54:55], v[62:63], v[52:53] op_sel:[0,0,1] op_sel_hi:[1,1,0] neg_lo:[0,0,1]
	s_nop 0
	s_waitcnt lgkmcnt(12)
	v_pk_add_f32 v[62:63], v[72:73], v[114:115]
	ds_read_b32 v128, v154 offset:7920
	ds_read_b32 v129, v154 offset:8176
	s_nop 0
	v_cvt_pk_bf16_f32 v146, v62, v63
	v_pk_mul_f32 v[52:53], v[56:57], v[62:63]
	s_nop 0
	v_pk_fma_f32 v[72:73], v[54:55], v[62:63], v[52:53] op_sel:[0,0,1] op_sel_hi:[1,1,0] neg_lo:[0,0,1]
	s_nop 0
	s_waitcnt lgkmcnt(12)
	v_pk_add_f32 v[62:63], v[72:73], v[116:117]
	s_nop 0
	v_cvt_pk_bf16_f32 v147, v62, v63
	v_pk_mul_f32 v[52:53], v[56:57], v[62:63]
	s_nop 0
	v_pk_fma_f32 v[72:73], v[54:55], v[62:63], v[52:53] op_sel:[0,0,1] op_sel_hi:[1,1,0] neg_lo:[0,0,1]
	s_nop 0
	s_waitcnt lgkmcnt(10)
	v_pk_add_f32 v[62:63], v[72:73], v[118:119]
	s_nop 0
	v_cvt_pk_bf16_f32 v148, v62, v63
	v_pk_mul_f32 v[52:53], v[56:57], v[62:63]
	s_nop 0
	v_pk_fma_f32 v[72:73], v[54:55], v[62:63], v[52:53] op_sel:[0,0,1] op_sel_hi:[1,1,0] neg_lo:[0,0,1]
	s_nop 0
	s_waitcnt lgkmcnt(8)
	v_pk_add_f32 v[62:63], v[72:73], v[120:121]
	s_nop 0
	v_cvt_pk_bf16_f32 v149, v62, v63
	v_pk_mul_f32 v[52:53], v[56:57], v[62:63]
	s_nop 0
	v_pk_fma_f32 v[72:73], v[54:55], v[62:63], v[52:53] op_sel:[0,0,1] op_sel_hi:[1,1,0] neg_lo:[0,0,1]
	s_nop 0
	s_waitcnt lgkmcnt(6)
	v_pk_add_f32 v[62:63], v[72:73], v[122:123]
	s_nop 0
	v_cvt_pk_bf16_f32 v150, v62, v63
	v_pk_mul_f32 v[52:53], v[56:57], v[62:63]
	s_nop 0
	v_pk_fma_f32 v[72:73], v[54:55], v[62:63], v[52:53] op_sel:[0,0,1] op_sel_hi:[1,1,0] neg_lo:[0,0,1]
	s_nop 0
	s_waitcnt lgkmcnt(4)
	v_pk_add_f32 v[62:63], v[72:73], v[124:125]
	s_nop 0
	v_cvt_pk_bf16_f32 v151, v62, v63
	v_pk_mul_f32 v[52:53], v[56:57], v[62:63]
	s_nop 0
	v_pk_fma_f32 v[72:73], v[54:55], v[62:63], v[52:53] op_sel:[0,0,1] op_sel_hi:[1,1,0] neg_lo:[0,0,1]
	s_nop 0
	s_waitcnt lgkmcnt(2)
	v_pk_add_f32 v[62:63], v[72:73], v[126:127]
	s_nop 0
	v_cvt_pk_bf16_f32 v152, v62, v63
	v_pk_mul_f32 v[52:53], v[56:57], v[62:63]
	s_nop 0
	v_pk_fma_f32 v[72:73], v[54:55], v[62:63], v[52:53] op_sel:[0,0,1] op_sel_hi:[1,1,0] neg_lo:[0,0,1]
	s_nop 0
	s_waitcnt lgkmcnt(0)
	v_pk_add_f32 v[62:63], v[72:73], v[128:129]
	s_nop 0
	v_cvt_pk_bf16_f32 v153, v62, v63
	ds_write_b32 v155, v138 offset:0
	ds_write_b32 v155, v139 offset:272
	ds_write_b32 v155, v140 offset:544
	ds_write_b32 v155, v141 offset:816
	ds_write_b32 v155, v142 offset:1088
	ds_write_b32 v155, v143 offset:1360
	ds_write_b32 v155, v144 offset:1632
	ds_write_b32 v155, v145 offset:1904
	ds_write_b32 v155, v146 offset:2176
	ds_write_b32 v155, v147 offset:2448
	ds_write_b32 v155, v148 offset:2720
	ds_write_b32 v155, v149 offset:2992
	ds_write_b32 v155, v150 offset:3264
	ds_write_b32 v155, v151 offset:3536
	ds_write_b32 v155, v152 offset:3808
	ds_write_b32 v155, v153 offset:4080
	s_waitcnt lgkmcnt(0)
	ds_read_b128 v[50:53], v69 offset:49152
	ds_read_b128 v[72:75], v69 offset:49216
	s_waitcnt lgkmcnt(1)
	v_mfma_f32_16x16x32_bf16 v[50:53], v[50:53], v[34:37], 0
	s_waitcnt lgkmcnt(0)
	v_mfma_f32_16x16x32_bf16 v[50:53], v[72:75], v[38:41], v[50:53]
	ds_read_b128 v[72:75], v69 offset:49280
	s_waitcnt lgkmcnt(0)
	v_mfma_f32_16x16x32_bf16 v[50:53], v[72:75], v[42:45], v[50:53]
	ds_read_b128 v[72:75], v69 offset:49344
	s_waitcnt lgkmcnt(0)
	v_mfma_f32_16x16x32_bf16 v[50:53], v[72:75], v[46:49], v[50:53]
	v_lshl_or_b32 v74, s35, 4, v87
	v_lshl_add_u32 v72, v74, 6, v88
	ds_read_b32 v72, v72 offset:16384
	s_add_i32 s35, s35, 1
	s_cmp_eq_u32 s35, 4
	s_waitcnt lgkmcnt(0)
	s_nop 1
	v_fma_f32 v50, v66, v72, v50
	v_mul_f32_e32 v72, 0x3d372713, v50
	v_mul_f32_e32 v72, v50, v72
	v_fma_f32 v72, v50, v72, v50
	v_mul_f32_e32 v72, 0x3f4c422a, v72
	v_add_f32_e32 v72, v72, v72
	v_mul_f32_e32 v72, 0x3fb8aa3b, v72
	v_exp_f32_e32 v72, v72
	v_mul_f32_e32 v50, 0.5, v50
	v_add_f32_e32 v72, 1.0, v72
	v_rcp_f32_e32 v72, v72
	s_nop 0
	v_fma_f32 v72, v72, -2.0, 1.0
	v_add_f32_e32 v72, 1.0, v72
	v_mul_f32_e32 v50, v50, v72
	v_or_b32_e32 v72, s25, v74
	v_ashrrev_i32_e32 v73, 31, v72
	v_lshlrev_b64 v[72:73], 10, v[72:73]
	v_cvt_pk_bf16_f32 v50, v50, 0
	v_lshl_add_u64 v[72:73], v[60:61], 0, v[72:73]
	global_store_short v[72:73], v50, off
	v_or_b32_e32 v50, 1, v74
	v_lshl_add_u32 v72, v50, 6, v88
	ds_read_b32 v72, v72 offset:16384
	v_or_b32_e32 v50, s25, v50
	s_waitcnt lgkmcnt(0)
	v_fma_f32 v51, v66, v72, v51
	v_mul_f32_e32 v72, 0x3d372713, v51
	v_mul_f32_e32 v72, v51, v72
	v_fma_f32 v72, v51, v72, v51
	v_mul_f32_e32 v72, 0x3f4c422a, v72
	v_add_f32_e32 v72, v72, v72
	v_mul_f32_e32 v72, 0x3fb8aa3b, v72
	v_exp_f32_e32 v72, v72
	v_mul_f32_e32 v51, 0.5, v51
	v_add_f32_e32 v72, 1.0, v72
	v_rcp_f32_e32 v72, v72
	s_nop 0
	v_fma_f32 v72, v72, -2.0, 1.0
	v_add_f32_e32 v72, 1.0, v72
	v_mul_f32_e32 v51, v51, v72
	v_cvt_pk_bf16_f32 v72, v51, 0
	v_ashrrev_i32_e32 v51, 31, v50
	v_lshlrev_b64 v[50:51], 10, v[50:51]
	v_lshl_add_u64 v[50:51], v[60:61], 0, v[50:51]
	global_store_short v[50:51], v72, off
	v_or_b32_e32 v50, 2, v74
	v_lshl_add_u32 v51, v50, 6, v88
	ds_read_b32 v51, v51 offset:16384
	v_or_b32_e32 v50, s25, v50
	s_waitcnt lgkmcnt(0)
	v_fma_f32 v51, v66, v51, v52
	v_mul_f32_e32 v52, 0x3d372713, v51
	v_mul_f32_e32 v52, v51, v52
	v_fma_f32 v52, v51, v52, v51
	v_mul_f32_e32 v52, 0x3f4c422a, v52
	v_add_f32_e32 v52, v52, v52
	v_mul_f32_e32 v52, 0x3fb8aa3b, v52
	v_exp_f32_e32 v52, v52
	v_mul_f32_e32 v51, 0.5, v51
	v_add_f32_e32 v52, 1.0, v52
	v_rcp_f32_e32 v52, v52
	s_nop 0
	v_fma_f32 v52, v52, -2.0, 1.0
	v_add_f32_e32 v52, 1.0, v52
	v_mul_f32_e32 v51, v51, v52
	v_cvt_pk_bf16_f32 v52, v51, 0
	v_ashrrev_i32_e32 v51, 31, v50
	v_lshlrev_b64 v[50:51], 10, v[50:51]
	v_lshl_add_u64 v[50:51], v[60:61], 0, v[50:51]
	global_store_short v[50:51], v52, off
	v_or_b32_e32 v50, 3, v74
	v_lshl_add_u32 v51, v50, 6, v88
	ds_read_b32 v51, v51 offset:16384
	v_or_b32_e32 v50, s25, v50
	s_waitcnt lgkmcnt(0)
	v_fmac_f32_e32 v53, v66, v51
	v_mul_f32_e32 v51, 0x3d372713, v53
	v_mul_f32_e32 v51, v53, v51
	v_fma_f32 v51, v53, v51, v53
	v_mul_f32_e32 v51, 0x3f4c422a, v51
	v_add_f32_e32 v51, v51, v51
	v_mul_f32_e32 v51, 0x3fb8aa3b, v51
	v_exp_f32_e32 v51, v51
	v_mul_f32_e32 v52, 0.5, v53
	v_add_f32_e32 v51, 1.0, v51
	v_rcp_f32_e32 v51, v51
	s_nop 0
	v_fma_f32 v51, v51, -2.0, 1.0
	v_add_f32_e32 v51, 1.0, v51
	v_mul_f32_e32 v51, v52, v51
	v_cvt_pk_bf16_f32 v52, v51, 0
	v_ashrrev_i32_e32 v51, 31, v50
	v_lshlrev_b64 v[50:51], 10, v[50:51]
	v_lshl_add_u64 v[50:51], v[60:61], 0, v[50:51]
	global_store_short v[50:51], v52, off
	s_waitcnt lgkmcnt(0)
	s_cbranch_scc0 .LBB0_982
	s_add_i32 s21, s21, 1
	s_cmp_eq_u32 s21, 4
	s_cbranch_scc0 .LBB0_981
	s_add_i32 s34, s34, s59
	s_cmpk_lt_i32 s34, 0x200
	s_barrier
	s_cbranch_scc1 .LBB0_944
	v_readlane_b32 s0, v253, 38
	v_readlane_b32 s8, v253, 46
	v_readlane_b32 s14, v253, 52
	v_readlane_b32 s9, v253, 47
	v_readlane_b32 s15, v253, 53
	s_add_u32 s8, s14, 0x34e00000
	v_readlane_b32 s10, v253, 48
	s_addc_u32 s9, s15, 0
	v_readlane_b32 s11, v253, 49
	v_readlane_b32 s12, v253, 50
	v_readlane_b32 s13, v253, 51
	s_add_u32 s10, s14, 0x9a00800
	s_addc_u32 s11, s15, 0
	v_readlane_b32 s12, v253, 6
	s_mov_b32 s13, s58
	v_readlane_b32 s1, v253, 39
	v_readlane_b32 s2, v253, 40
	v_readlane_b32 s3, v253, 41
	v_readlane_b32 s4, v253, 42
	v_readlane_b32 s5, v253, 43
	v_readlane_b32 s6, v253, 44
	v_readlane_b32 s7, v253, 45
